# retention: static s_setprio 1 for waves 4-7 during the phase (on v34)
# baseline (speedup 1.0000x reference)
; #define LAS __attribute__((address_space(3)))
; __device__ __forceinline__ int lane_id_asm() { int l; asm volatile("v_mbcnt_lo_u32_b32 %0, -1, 0\n\tv_mbcnt_hi_u32_b32 %0, -1, %0" : "=v"(l)); return l; }
; __device__ __forceinline__ void ret_mfma(const Params& P, LAS unsigned char* lds, int wave) {
;     ...
;     const int lane = lane_id_asm(), t = wave * 64 + lane, q32 = lane & 31, hf = lane >> 5, i16 = lane & 15, blk = (lane >> 4) & 1;
;     const int trrow = 8 * hf + (i16 >> 2), trcol = (16 * blk + 4 * (i16 & 3)) * 2;
;     for (int unit = blockIdx.x; unit < 256; unit += gridDim.x) {
;         const int xcd_ = unit & 7, idx_ = unit >> 3, bh = xcd_ * 4 + (idx_ >> 3), slice = idx_ & 7, b = bh >> 2, hh = bh & 3;
;         const float gam = 1.f - exp2f(-5.f - (float)hh), lg = log2f(gam), g64 = exp2f(lg * 64.f);
;         for (int i = t; i < 33792 / 16; i += NTHREADS) *(LAS u32x4*)(lds + ST_OFF + i * 16) = (u32x4){0u, 0u, 0u, 0u};
;         f32x16 st[2];
; #pragma unroll
;         for (int a = 0; a < 2; ++a)
; #pragma unroll
;             for (int i = 0; i < 16; ++i) st[a][i] = 0.f;
;         const size_t rb = (size_t)b * SEQ;
;         float dec[16];
;         { const int mblk = (wave & 3) >> 1, nblk = wave & 1, n = nblk * 32 + q32;
; #pragma unroll
;           for (int i = 0; i < 16; ++i) { const int mm = mblk * 32 + 8 * (i >> 2) + 4 * hf + (i & 3); const int dist = n > mm ? n - mm : mm - n;
;               dec[i] = wave < 4 ? __builtin_amdgcn_exp2f(lg * (float)(dist - (63 - mm))) : __builtin_amdgcn_exp2f(lg * (float)(n + 1)); } }
;         u32x4 pq[4], pkk[4], pvv;
;         const int vr = t >> 3, vc = t & 7;
; #pragma unroll
;         for (int i = 0; i < 4; ++i) { const int id = t + 512 * i, r = id >> 5, ch = id & 31;
;             pq[i] = *(const u32x4*)(QK + (rb + r) * 2048 + hh * 256 + ch * 8); pkk[i] = *(const u32x4*)(QK + (rb + r) * 2048 + 1024 + hh * 256 + ch * 8); }
;         pvv = *(const u32x4*)(V + (rb + vr) * 2048 + hh * 512 + slice * 64 + vc * 8);
.LBB0_246:
	s_or_b64 exec, exec, s[50:51]
	s_add_u32 s60, s54, 0x1f000000
	s_addc_u32 s61, s55, 0
	s_cmpk_gt_i32 s2, 0xff
	s_waitcnt lgkmcnt(0)
	s_barrier
	v_mbcnt_lo_u32_b32 v0, -1, 0
	v_mbcnt_hi_u32_b32 v0, -1, v0
	s_cbranch_scc1 .LBB0_270
	v_ashrrev_i32_e32 v3, 5, v0
	v_and_b32_e32 v8, 31, v0
	v_readlane_b32 s4, v254, 4
	s_cmpk_lt_u32 s3, 0x100
	v_lshlrev_b32_e32 v5, 3, v3
	v_lshrrev_b32_e32 v2, 2, v0
	v_and_or_b32 v84, s4, 32, v8
	s_cselect_b64 s[4:5], -1, 0
	s_cmpk_gt_u32 s3, 0xff
	v_add_u32_e32 v1, s64, v0
	v_and_or_b32 v6, v2, 3, v5
	v_lshlrev_b32_e32 v2, 2, v0
	v_and_b32_e32 v4, 16, v0
	s_cselect_b64 s[10:11], -1, 0
	s_lshl_b32 s6, s33, 4
	v_and_or_b32 v2, v2, 12, v4
	s_and_b32 s6, s6, 32
	v_lshlrev_b32_e32 v86, 2, v3
	v_ashrrev_i32_e32 v88, 3, v1
	s_movk_i32 s9, 0xc0
	v_lshlrev_b32_e32 v7, 1, v2
	v_add_u32_e32 v9, s6, v86
	v_mul_lo_u32 v13, v88, s9
	s_add_i32 s6, 0, 0x10800
	v_add_u32_e32 v13, s6, v13
	v_add_u32_e32 v148, s6, v7
	s_add_i32 s6, s64, 0
	s_add_i32 s16, 0, 0x16800
	s_add_i32 s7, 0, 0x1ec00
	v_add_u32_e32 v7, s6, v7
	s_add_i32 s6, s16, s64
	v_lshlrev_b32_e32 v149, 4, v3
	v_mul_u32_u24_e32 v15, 0x210, v84
	v_lshl_add_u32 v14, v8, 1, s6
	v_add3_u32 v150, 0, v15, v149
	s_movk_i32 s6, 0x90
	v_mov_b32_e32 v15, s7
	v_add_u32_e32 v2, 1, v84
	v_mad_u32_u24 v151, v84, s6, v15
	s_add_i32 s6, s33, -4
	v_cvt_f32_ubyte0_e32 v85, v2
	v_and_b32_e32 v10, 7, v0
	v_lshlrev_b32_e32 v2, 3, v0
	v_lshlrev_b32_e32 v11, 4, v0
	s_lshr_b32 s14, s6, 1
	v_cmp_lt_u32_e64 s[6:7], 31, v0
	v_sub_u32_e32 v0, v84, v9
	v_sub_u32_e32 v16, 0, v0
	v_max_i32_e32 v16, v0, v16
	s_movk_i32 s21, 0xffc1
	v_add3_u32 v16, v9, v16, s21
	v_cvt_f32_i32_e32 v152, v16
	v_xad_u32 v16, v9, -1, v84
	v_sub_u32_e32 v17, 0, v16
	v_max_i32_e32 v16, v16, v17
	s_movk_i32 s21, 0xffc2
	v_add3_u32 v16, v9, v16, s21
	v_cvt_f32_i32_e32 v153, v16
	v_add_u32_e32 v16, -2, v0
	v_sub_u32_e32 v17, 2, v0
	v_max_i32_e32 v16, v16, v17
	s_movk_i32 s21, 0xffc3
	v_add3_u32 v16, v9, v16, s21
	v_cvt_f32_i32_e32 v154, v16
	v_add_u32_e32 v16, -3, v0
	v_sub_u32_e32 v17, 3, v0
	v_max_i32_e32 v16, v16, v17
	s_movk_i32 s21, 0xffc4
	v_add3_u32 v16, v9, v16, s21
	v_cvt_f32_i32_e32 v155, v16
	v_add_u32_e32 v16, -8, v0
	v_sub_u32_e32 v17, 8, v0
	v_max_i32_e32 v16, v16, v17
	s_movk_i32 s21, 0xffc9
	v_add3_u32 v16, v9, v16, s21
	v_cvt_f32_i32_e32 v156, v16
	v_add_u32_e32 v16, -9, v0
	v_sub_u32_e32 v17, 9, v0
	v_max_i32_e32 v16, v16, v17
	s_movk_i32 s21, 0xffca
	v_add3_u32 v16, v9, v16, s21
	v_cvt_f32_i32_e32 v157, v16
	v_add_u32_e32 v16, -10, v0
	v_sub_u32_e32 v17, 10, v0
	v_max_i32_e32 v16, v16, v17
	s_movk_i32 s21, 0xffcb
	v_add3_u32 v16, v9, v16, s21
	v_cvt_f32_i32_e32 v158, v16
	v_add_u32_e32 v16, -11, v0
	v_sub_u32_e32 v17, 11, v0
	v_max_i32_e32 v16, v16, v17
	s_movk_i32 s21, 0xffcc
	v_add3_u32 v16, v9, v16, s21
	v_cvt_f32_i32_e32 v159, v16
	v_add_u32_e32 v16, -16, v0
	v_sub_u32_e32 v17, 16, v0
	v_max_i32_e32 v16, v16, v17
	s_movk_i32 s21, 0xffd1
	v_add3_u32 v16, v9, v16, s21
	v_cvt_f32_i32_e32 v160, v16
	v_subrev_u32_e32 v16, 17, v0
	v_sub_u32_e32 v17, 17, v0
	v_max_i32_e32 v16, v16, v17
	s_movk_i32 s21, 0xffd2
	v_add3_u32 v16, v9, v16, s21
	v_cvt_f32_i32_e32 v161, v16
	v_subrev_u32_e32 v16, 18, v0
	v_sub_u32_e32 v17, 18, v0
	v_max_i32_e32 v16, v16, v17
	s_movk_i32 s21, 0xffd3
	v_add3_u32 v16, v9, v16, s21
	v_cvt_f32_i32_e32 v162, v16
	v_subrev_u32_e32 v16, 19, v0
	v_sub_u32_e32 v17, 19, v0
	v_max_i32_e32 v16, v16, v17
	s_movk_i32 s21, 0xffd4
	v_add3_u32 v16, v9, v16, s21
	v_cvt_f32_i32_e32 v163, v16
	v_subrev_u32_e32 v16, 24, v0
	v_sub_u32_e32 v17, 24, v0
	v_max_i32_e32 v16, v16, v17
	s_movk_i32 s21, 0xffd9
	v_add3_u32 v16, v9, v16, s21
	v_cvt_f32_i32_e32 v164, v16
	v_subrev_u32_e32 v16, 25, v0
	v_sub_u32_e32 v17, 25, v0
	v_max_i32_e32 v16, v16, v17
	s_movk_i32 s21, 0xffda
	v_add3_u32 v16, v9, v16, s21
	v_cvt_f32_i32_e32 v165, v16
	v_subrev_u32_e32 v16, 26, v0
	v_sub_u32_e32 v17, 26, v0
	v_max_i32_e32 v16, v16, v17
	s_movk_i32 s21, 0xffdb
	v_add3_u32 v16, v9, v16, s21
	v_cvt_f32_i32_e32 v166, v16
	v_subrev_u32_e32 v16, 27, v0
	v_sub_u32_e32 v0, 27, v0
	v_max_i32_e32 v0, v16, v0
	s_movk_i32 s21, 0xffdc
	v_add3_u32 v0, v9, v0, s21
	s_movk_i32 s8, 0x840
	s_lshr_b32 s18, s3, 7
	v_cvt_f32_i32_e32 v167, v0
	v_add_u32_e32 v0, 0x200, v1
	v_cmp_gt_i32_e64 s[0:1], s8, v1
	v_ashrrev_i32_e32 v94, 5, v0
	v_add_u32_e32 v0, 0x400, v1
	v_mul_lo_u32 v3, v3, s8
	s_mul_i32 s8, s18, 0x4200
	s_movk_i32 s17, 0x210
	v_ashrrev_i32_e32 v92, 5, v1
	v_ashrrev_i32_e32 v96, 5, v0
	v_add_u32_e32 v0, 0x600, v1
	v_add_u32_e32 v169, 0xfffffe00, v1
	v_mov_b32_e32 v1, s8
	v_and_b32_e32 v2, 0xf8, v2
	v_and_b32_e32 v12, 0x1f0, v11
	v_ashrrev_i32_e32 v98, 5, v0
	v_mad_u32_u24 v1, v8, s17, v1
	s_mov_b32 s15, 0
	v_mov_b32_e32 v91, 0
	v_lshlrev_b32_e32 v4, 3, v10
	v_add_u32_e32 v12, 0, v12
	v_lshlrev_b32_e32 v10, 4, v10
	s_lshl_b32 s19, s18, 6
	v_add_u32_e32 v5, v151, v5
	v_lshl_add_u32 v15, s14, 6, v148
	s_lshl_b32 s20, s14, 5
	v_mul_lo_u32 v0, v92, s17
	v_mul_lo_u32 v9, v94, s17
	v_mul_lo_u32 v16, v96, s17
	v_mul_lo_u32 v17, v98, s17
	v_mul_lo_u32 v168, v6, s9
	v_mul_lo_u32 v6, v6, s17
	v_lshlrev_b32_e32 v90, 1, v2
	s_add_i32 s16, s16, s68
	v_add3_u32 v1, v1, v149, 0
	v_ashrrev_i32_e32 v89, 31, v88
	v_ashrrev_i32_e32 v87, 31, v86
	v_ashrrev_i32_e32 v93, 31, v92
	v_ashrrev_i32_e32 v95, 31, v94
	v_ashrrev_i32_e32 v97, 31, v96
	v_ashrrev_i32_e32 v99, 31, v98
	v_lshl_add_u64 v[100:101], s[44:45], 0, v[90:91]
	v_add_u32_e32 v170, s16, v11
	v_add_u32_e32 v171, 0xe400, v1
	v_add_u32_e32 v172, 0x8400, v1
	s_movk_i32 s24, 0x63f
	s_mov_b32 s25, 0xc2fc0000
	s_mov_b32 s26, 0x800000
	v_lshlrev_b32_e32 v90, 1, v2
	v_lshlrev_b32_e32 v102, 1, v4
	s_lshl_b64 s[16:17], s[14:15], 2
	s_lshl_b32 s27, s20, 1
	v_add_u32_e32 v173, v12, v0
	v_add_u32_e32 v174, v12, v9
	v_add_u32_e32 v175, v12, v16
	v_add_u32_e32 v176, v12, v17
	v_add_u32_e32 v177, v13, v10
	v_add_u32_e32 v178, s19, v5
	v_add_u32_e32 v179, v7, v6
	v_add_u32_e32 v180, v14, v3
	v_add_u32_e32 v181, v15, v168
	v_mov_b32_e32 v186, v91
	v_mov_b32_e32 v187, v91
	v_mov_b32_e32 v188, v91
	v_mov_b32_e32 v189, v91
	v_mov_b32_e32 v182, 0x42800000
	v_mov_b32_e32 v183, 0x42000000
	v_mbcnt_hi_u32_b32 v184, -1, v244
	v_and_b32_e32 v242, 31, v184
	v_mul_u32_u24_e32 v242, 0x210, v242
	v_lshrrev_b32_e32 v103, 5, v184
	v_lshl_add_u32 v242, v103, 3, v242
	v_add_u32_e32 v242, s64, v242
	v_add_u32_e32 v242, 0x16800, v242
	s_mov_b32 s28, s2
	s_cmp_lg_u64 s[10:11], 0
	s_cbranch_scc0 .Lret_noprio
	s_setprio 1
